# v88: XCD-local barriers at out->up and up->down seams + two items in flight per iteration in the deferred conversion loops (W_dn, W_out, W_up)
# baseline (speedup 1.0000x reference)
; template <int MODE, int K, int N>
; __device__ __forceinline__ void conv_blocked(const float* __restrict__ W, bf16* D, const float* __restrict__ gk, unsigned gtid, unsigned nthr, LAS unsigned char* scr  ) {
;     ...
;     for (unsigned it = gtid; it < items; it += nthr) {
;         const unsigned kb = it / (unsigned)N; const int n = (int)(it - kb * (unsigned)N), k0 = (int)kb * 32;
;         if (MODE == 1 && n >= C_U && n < C_GB) continue;
;         const float* src = W + (size_t)k0 * N + n;
;         float v[32];
; #pragma unroll
;         for (int i = 0; i < 32; ++i) v[i] = __builtin_nontemporal_load(src + (size_t)i * N);
.Lca_35:
	s_mul_i32 s10, s28, 0x17000000
	s_add_u32 s10, s58, s10
	s_addc_u32 s11, s59, 0
	s_lshl_b64 s[44:45], s[28:29], 28
	v_lshl_add_u64 v[8:9], s[10:11], 0, v[4:5]
	s_and_saveexec_b64 s[10:11], s[4:5]
	s_cbranch_execz .Lca_38
	s_add_u32 s42, s22, s44
	s_addc_u32 s43, s23, s45
	v_lshl_add_u64 v[10:11], v[8:9], 0, s[36:37]
	s_mov_b64 s[46:47], 0
	v_mov_b32_e32 v12, v3
	v_mov_b32_e32 v13, v1
	v_mov_b32_e32 v107, 0
.Lca_37:
	v_and_b32_e32 v6, 0x3fe0000, v12
	v_and_b32_e32 v22, 0xfff, v13
	v_lshlrev_b32_e32 v6, 2, v6
	v_lshl_add_u64 v[14:15], s[42:43], 0, v[6:7]
	v_lshlrev_b32_e32 v6, 2, v22
	v_lshl_add_u64 v[14:15], v[14:15], 0, v[6:7]
	v_add_co_u32_e32 v16, vcc, 0x4000, v14
	global_load_dword v23, v[14:15], off nt
	s_nop 0
	v_addc_co_u32_e32 v17, vcc, 0, v15, vcc
	v_add_co_u32_e32 v18, vcc, 0x8000, v14
	global_load_dword v24, v[16:17], off nt
	s_nop 0
	v_addc_co_u32_e32 v19, vcc, 0, v15, vcc
	v_add_co_u32_e32 v16, vcc, 0xc000, v14
	v_lshrrev_b32_e32 v6, 2, v13
	s_nop 0
	v_addc_co_u32_e32 v17, vcc, 0, v15, vcc
	v_add_co_u32_e32 v20, vcc, 0x10000, v14
	global_load_dword v25, v[18:19], off nt
	global_load_dword v26, v[16:17], off nt
	v_addc_co_u32_e32 v21, vcc, 0, v15, vcc
	v_add_co_u32_e32 v16, vcc, 0x14000, v14
	v_and_b32_e32 v6, 0x7fc00, v6
	s_nop 0
	v_addc_co_u32_e32 v17, vcc, 0, v15, vcc
	v_add_co_u32_e32 v18, vcc, 0x18000, v14
	global_load_dword v27, v[20:21], off nt
	global_load_dword v28, v[16:17], off nt
	v_addc_co_u32_e32 v19, vcc, 0, v15, vcc
	v_add_co_u32_e32 v16, vcc, 0x1c000, v14
	v_lshl_add_u64 v[30:31], v[10:11], 0, v[6:7]
	s_nop 0
	v_addc_co_u32_e32 v17, vcc, 0, v15, vcc
	v_add_co_u32_e32 v20, vcc, 0x20000, v14
	global_load_dword v29, v[18:19], off nt
	global_load_dword v40, v[16:17], off nt
	v_addc_co_u32_e32 v21, vcc, 0, v15, vcc
	v_add_co_u32_e32 v16, vcc, 0x24000, v14
	v_add_u32_e32 v13, s0, v13
	s_nop 0
	v_addc_co_u32_e32 v17, vcc, 0, v15, vcc
	v_add_co_u32_e32 v18, vcc, 0x28000, v14
	global_load_dword v41, v[20:21], off nt
	global_load_dword v42, v[16:17], off nt
	v_addc_co_u32_e32 v19, vcc, 0, v15, vcc
	v_add_co_u32_e32 v16, vcc, 0x2c000, v14
	v_add_u32_e32 v12, s62, v12
	s_nop 0
	v_addc_co_u32_e32 v17, vcc, 0, v15, vcc
	v_add_co_u32_e32 v20, vcc, 0x30000, v14
	global_load_dword v43, v[18:19], off nt
	global_load_dword v49, v[16:17], off nt
	v_addc_co_u32_e32 v21, vcc, 0, v15, vcc
	v_add_co_u32_e32 v16, vcc, 0x34000, v14
	s_nop 1
	v_addc_co_u32_e32 v17, vcc, 0, v15, vcc
	v_add_co_u32_e32 v18, vcc, 0x38000, v14
	global_load_dword v50, v[20:21], off nt
	global_load_dword v51, v[16:17], off nt
	v_addc_co_u32_e32 v19, vcc, 0, v15, vcc
	v_add_co_u32_e32 v16, vcc, 0x3c000, v14
	s_nop 1
	v_addc_co_u32_e32 v17, vcc, 0, v15, vcc
	v_add_co_u32_e32 v20, vcc, 0x40000, v14
	global_load_dword v52, v[18:19], off nt
	global_load_dword v53, v[16:17], off nt
	v_addc_co_u32_e32 v21, vcc, 0, v15, vcc
	v_add_co_u32_e32 v16, vcc, 0x44000, v14
	s_nop 1
	v_addc_co_u32_e32 v17, vcc, 0, v15, vcc
	v_add_co_u32_e32 v18, vcc, 0x48000, v14
	global_load_dword v54, v[20:21], off nt
	global_load_dword v55, v[16:17], off nt
	v_addc_co_u32_e32 v19, vcc, 0, v15, vcc
	v_add_co_u32_e32 v16, vcc, 0x4c000, v14
	s_nop 1
	v_addc_co_u32_e32 v17, vcc, 0, v15, vcc
	v_add_co_u32_e32 v20, vcc, 0x50000, v14
	global_load_dword v56, v[18:19], off nt
	global_load_dword v57, v[16:17], off nt
	v_addc_co_u32_e32 v21, vcc, 0, v15, vcc
	v_add_co_u32_e32 v16, vcc, 0x54000, v14
	s_nop 1
	v_addc_co_u32_e32 v17, vcc, 0, v15, vcc
	v_add_co_u32_e32 v18, vcc, 0x58000, v14
	global_load_dword v58, v[20:21], off nt
	global_load_dword v59, v[16:17], off nt
	v_addc_co_u32_e32 v19, vcc, 0, v15, vcc
	v_add_co_u32_e32 v16, vcc, 0x5c000, v14
	s_nop 1
	v_addc_co_u32_e32 v17, vcc, 0, v15, vcc
	v_add_co_u32_e32 v20, vcc, 0x60000, v14
	global_load_dword v60, v[18:19], off nt
	global_load_dword v61, v[16:17], off nt
	v_addc_co_u32_e32 v21, vcc, 0, v15, vcc
	v_add_co_u32_e32 v16, vcc, 0x64000, v14
	s_nop 1
	v_addc_co_u32_e32 v17, vcc, 0, v15, vcc
	v_add_co_u32_e32 v18, vcc, 0x68000, v14
	global_load_dword v62, v[20:21], off nt
	global_load_dword v63, v[16:17], off nt
	v_addc_co_u32_e32 v19, vcc, 0, v15, vcc
	v_add_co_u32_e32 v16, vcc, 0x6c000, v14
	s_nop 1
	v_addc_co_u32_e32 v17, vcc, 0, v15, vcc
	v_add_co_u32_e32 v20, vcc, 0x70000, v14
	global_load_dword v64, v[18:19], off nt
	global_load_dword v65, v[16:17], off nt
	v_addc_co_u32_e32 v21, vcc, 0, v15, vcc
	v_add_co_u32_e32 v16, vcc, 0x74000, v14
	s_nop 1
	v_addc_co_u32_e32 v17, vcc, 0, v15, vcc
	v_add_co_u32_e32 v18, vcc, 0x78000, v14
	global_load_dword v66, v[20:21], off nt
	global_load_dword v67, v[16:17], off nt
	v_addc_co_u32_e32 v19, vcc, 0, v15, vcc
	v_add_co_u32_e32 v14, vcc, 0x7c000, v14
	s_nop 1
	v_addc_co_u32_e32 v15, vcc, 0, v15, vcc
	global_load_dword v68, v[18:19], off nt
	global_load_dword v69, v[14:15], off nt
	v_cmp_ge_u32_e32 vcc, s63, v13
	v_subrev_u32_e32 v112, s62, v12
	v_subrev_u32_e32 v113, s0, v13
	s_mov_b64 s[98:99], vcc
	v_cndmask_b32_e32 v112, v112, v12, vcc
	v_cndmask_b32_e32 v113, v113, v13, vcc
	v_add_u32_e32 v13, s0, v13
	v_add_u32_e32 v12, s62, v12
	v_and_b32_e32 v106, 0x3fe0000, v112
	v_and_b32_e32 v122, 0xfff, v113
	v_lshlrev_b32_e32 v106, 2, v106
	v_lshl_add_u64 v[114:115], s[42:43], 0, v[106:107]
	v_lshlrev_b32_e32 v106, 2, v122
	v_lshl_add_u64 v[114:115], v[114:115], 0, v[106:107]
	v_add_co_u32_e32 v116, vcc, 0x4000, v114
	global_load_dword v123, v[114:115], off nt
	s_nop 0
	v_addc_co_u32_e32 v117, vcc, 0, v115, vcc
	v_add_co_u32_e32 v118, vcc, 0x8000, v114
	global_load_dword v124, v[116:117], off nt
	s_nop 0
	v_addc_co_u32_e32 v119, vcc, 0, v115, vcc
	v_add_co_u32_e32 v116, vcc, 0xc000, v114
; __device__ __forceinline__ unsigned cvt_pk_bf16(float lo, float hi) { f32x2 v = {lo, hi}; bf16x2_t b = __builtin_convertvector(v, bf16x2_t); return __builtin_bit_cast(unsigned, b); }
; #define LAS __attribute__((address_space(3)))
; template <int MODE, int K, int N>
; __device__ __forceinline__ void conv_blocked(const float* __restrict__ W, bf16* D, const float* __restrict__ gk, unsigned gtid, unsigned nthr, LAS unsigned char* scr  ) {
;     ...
;     for (unsigned it = gtid; it < items; it += nthr) {
;         const unsigned kb = it / (unsigned)N; const int n = (int)(it - kb * (unsigned)N), k0 = (int)kb * 32;
;         if (MODE == 1 && n >= C_U && n < C_GB) continue;
;         const float* src = W + (size_t)k0 * N + n;
;         float v[32];
; #pragma unroll
;         for (int i = 0; i < 32; ++i) v[i] = __builtin_nontemporal_load(src + (size_t)i * N);
;         if (gk) {
; #pragma unroll
;             for (int i = 0; i < 32; ++i) v[i] *= gk[k0 + i];
;         }
;         const int rho = pg8::p32inv(lane & 31), half = lane >> 5;
; #pragma unroll
;         for (int c = 0; c < 4; ++c) { v4u o; o.x = cvt_pk_bf16(v[8 * c], v[8 * c + 1]); o.y = cvt_pk_bf16(v[8 * c + 2], v[8 * c + 3]); o.z = cvt_pk_bf16(v[8 * c + 4], v[8 * c + 5]); o.w = cvt_pk_bf16(v[8 * c + 6], v[8 * c + 7]);
;             *(LAS v4u*)(scr + (half * 32 + rho) * 64 + ((c * 16) ^ ((rho & 8) << 2))) = o; }
;         const int nb = n - lane;
; #pragma unroll
;         for (int i = 0; i < 4; ++i) { const int h2 = i >> 1, b2 = i & 1; const int gp = ((MODE == 1) ? nperm(nb + 32 * h2) : nb + 32 * h2) & ~31;
;             const v4u o = *(const LAS v4u*)(scr + (h2 * 32 + b2 * 16) * 64 + lane * 16);
;             *(v4u*)((unsigned char*)D + ((size_t)((gp >> 4) + b2) * (K >> 5) + (size_t)(k0 >> 5)) * 1024 + lane * 16) = o; }
	v_lshrrev_b32_e32 v106, 2, v113
	s_nop 0
	v_addc_co_u32_e32 v117, vcc, 0, v115, vcc
	v_add_co_u32_e32 v120, vcc, 0x10000, v114
	global_load_dword v125, v[118:119], off nt
	global_load_dword v126, v[116:117], off nt
	v_addc_co_u32_e32 v121, vcc, 0, v115, vcc
	v_add_co_u32_e32 v116, vcc, 0x14000, v114
	v_and_b32_e32 v106, 0x7fc00, v106
	s_nop 0
	v_addc_co_u32_e32 v117, vcc, 0, v115, vcc
	v_add_co_u32_e32 v118, vcc, 0x18000, v114
	global_load_dword v127, v[120:121], off nt
	global_load_dword v128, v[116:117], off nt
	v_addc_co_u32_e32 v119, vcc, 0, v115, vcc
	v_add_co_u32_e32 v116, vcc, 0x1c000, v114
	v_lshl_add_u64 v[130:131], v[10:11], 0, v[106:107]
	s_nop 0
	v_addc_co_u32_e32 v117, vcc, 0, v115, vcc
	v_add_co_u32_e32 v120, vcc, 0x20000, v114
	global_load_dword v129, v[118:119], off nt
	global_load_dword v140, v[116:117], off nt
	v_addc_co_u32_e32 v121, vcc, 0, v115, vcc
	v_add_co_u32_e32 v116, vcc, 0x24000, v114
	v_add_u32_e32 v113, s0, v113
	s_nop 0
	v_addc_co_u32_e32 v117, vcc, 0, v115, vcc
	v_add_co_u32_e32 v118, vcc, 0x28000, v114
	global_load_dword v141, v[120:121], off nt
	global_load_dword v142, v[116:117], off nt
	v_addc_co_u32_e32 v119, vcc, 0, v115, vcc
	v_add_co_u32_e32 v116, vcc, 0x2c000, v114
	v_add_u32_e32 v112, s62, v112
	s_nop 0
	v_addc_co_u32_e32 v117, vcc, 0, v115, vcc
	v_add_co_u32_e32 v120, vcc, 0x30000, v114
	global_load_dword v143, v[118:119], off nt
	global_load_dword v149, v[116:117], off nt
	v_addc_co_u32_e32 v121, vcc, 0, v115, vcc
	v_add_co_u32_e32 v116, vcc, 0x34000, v114
	s_nop 1
	v_addc_co_u32_e32 v117, vcc, 0, v115, vcc
	v_add_co_u32_e32 v118, vcc, 0x38000, v114
	global_load_dword v150, v[120:121], off nt
	global_load_dword v151, v[116:117], off nt
	v_addc_co_u32_e32 v119, vcc, 0, v115, vcc
	v_add_co_u32_e32 v116, vcc, 0x3c000, v114
	s_nop 1
	v_addc_co_u32_e32 v117, vcc, 0, v115, vcc
	v_add_co_u32_e32 v120, vcc, 0x40000, v114
	global_load_dword v152, v[118:119], off nt
	global_load_dword v153, v[116:117], off nt
	v_addc_co_u32_e32 v121, vcc, 0, v115, vcc
	v_add_co_u32_e32 v116, vcc, 0x44000, v114
	s_nop 1
	v_addc_co_u32_e32 v117, vcc, 0, v115, vcc
	v_add_co_u32_e32 v118, vcc, 0x48000, v114
	global_load_dword v154, v[120:121], off nt
	global_load_dword v155, v[116:117], off nt
	v_addc_co_u32_e32 v119, vcc, 0, v115, vcc
	v_add_co_u32_e32 v116, vcc, 0x4c000, v114
	s_nop 1
	v_addc_co_u32_e32 v117, vcc, 0, v115, vcc
	v_add_co_u32_e32 v120, vcc, 0x50000, v114
	global_load_dword v156, v[118:119], off nt
	global_load_dword v157, v[116:117], off nt
	v_addc_co_u32_e32 v121, vcc, 0, v115, vcc
	v_add_co_u32_e32 v116, vcc, 0x54000, v114
	s_nop 1
	v_addc_co_u32_e32 v117, vcc, 0, v115, vcc
	v_add_co_u32_e32 v118, vcc, 0x58000, v114
	global_load_dword v158, v[120:121], off nt
	global_load_dword v159, v[116:117], off nt
	v_addc_co_u32_e32 v119, vcc, 0, v115, vcc
	v_add_co_u32_e32 v116, vcc, 0x5c000, v114
	s_nop 1
	v_addc_co_u32_e32 v117, vcc, 0, v115, vcc
	v_add_co_u32_e32 v120, vcc, 0x60000, v114
	global_load_dword v160, v[118:119], off nt
	global_load_dword v161, v[116:117], off nt
	v_addc_co_u32_e32 v121, vcc, 0, v115, vcc
	v_add_co_u32_e32 v116, vcc, 0x64000, v114
	s_nop 1
	v_addc_co_u32_e32 v117, vcc, 0, v115, vcc
	v_add_co_u32_e32 v118, vcc, 0x68000, v114
	global_load_dword v162, v[120:121], off nt
	global_load_dword v163, v[116:117], off nt
	v_addc_co_u32_e32 v119, vcc, 0, v115, vcc
	v_add_co_u32_e32 v116, vcc, 0x6c000, v114
	s_nop 1
	v_addc_co_u32_e32 v117, vcc, 0, v115, vcc
	v_add_co_u32_e32 v120, vcc, 0x70000, v114
	global_load_dword v164, v[118:119], off nt
	global_load_dword v165, v[116:117], off nt
	v_addc_co_u32_e32 v121, vcc, 0, v115, vcc
	v_add_co_u32_e32 v116, vcc, 0x74000, v114
	s_nop 1
	v_addc_co_u32_e32 v117, vcc, 0, v115, vcc
	v_add_co_u32_e32 v118, vcc, 0x78000, v114
	s_waitcnt vmcnt(59)
	global_load_dword v166, v[120:121], off nt
	global_load_dword v167, v[116:117], off nt
	v_addc_co_u32_e32 v119, vcc, 0, v115, vcc
	v_add_co_u32_e32 v114, vcc, 0x7c000, v114
	s_nop 1
	v_addc_co_u32_e32 v115, vcc, 0, v115, vcc
	global_load_dword v168, v[118:119], off nt
	global_load_dword v169, v[114:115], off nt
	v_sub_u32_e32 v14, v22, v2
	v_ashrrev_i32_e32 v15, 4, v14
	v_add_u32_e32 v17, 32, v14
	v_and_b32_e32 v14, -2, v15
	v_ashrrev_i32_e32 v19, 4, v17
	v_or_b32_e32 v16, 1, v15
	v_ashrrev_i32_e32 v15, 31, v14
	v_and_b32_e32 v18, -2, v19
	v_ashrrev_i32_e32 v17, 31, v16
	v_or_b32_e32 v20, 1, v19
	v_lshlrev_b64 v[14:15], 19, v[14:15]
	v_ashrrev_i32_e32 v19, 31, v18
	v_lshlrev_b64 v[16:17], 19, v[16:17]
	v_lshl_add_u64 v[32:33], v[30:31], 0, v[14:15]
	v_lshlrev_b64 v[14:15], 19, v[18:19]
	v_lshl_add_u64 v[34:35], v[30:31], 0, v[16:17]
	v_lshl_add_u64 v[38:39], v[30:31], 0, v[14:15]
	s_waitcnt vmcnt(62)
; __device__ __forceinline__ unsigned cvt_pk_bf16(float lo, float hi) { f32x2 v = {lo, hi}; bf16x2_t b = __builtin_convertvector(v, bf16x2_t); return __builtin_bit_cast(unsigned, b); }
; #define LAS __attribute__((address_space(3)))
; template <int MODE, int K, int N>
; __device__ __forceinline__ void conv_blocked(const float* __restrict__ W, bf16* D, const float* __restrict__ gk, unsigned gtid, unsigned nthr, LAS unsigned char* scr  ) {
;     ...
;         const int rho = pg8::p32inv(lane & 31), half = lane >> 5;
; #pragma unroll
;         for (int c = 0; c < 4; ++c) { v4u o; o.x = cvt_pk_bf16(v[8 * c], v[8 * c + 1]); o.y = cvt_pk_bf16(v[8 * c + 2], v[8 * c + 3]); o.z = cvt_pk_bf16(v[8 * c + 4], v[8 * c + 5]); o.w = cvt_pk_bf16(v[8 * c + 6], v[8 * c + 7]);
;             *(LAS v4u*)(scr + (half * 32 + rho) * 64 + ((c * 16) ^ ((rho & 8) << 2))) = o; }
;         const int nb = n - lane;
; #pragma unroll
;         for (int i = 0; i < 4; ++i) { const int h2 = i >> 1, b2 = i & 1; const int gp = ((MODE == 1) ? nperm(nb + 32 * h2) : nb + 32 * h2) & ~31;
;             const v4u o = *(const LAS v4u*)(scr + (h2 * 32 + b2 * 16) * 64 + lane * 16);
;             *(v4u*)((unsigned char*)D + ((size_t)((gp >> 4) + b2) * (K >> 5) + (size_t)(k0 >> 5)) * 1024 + lane * 16) = o; }
;         asm volatile("s_waitcnt lgkmcnt(0)" ::: "memory");
	v_cvt_pk_bf16_f32 v14, v23, v24
	s_waitcnt vmcnt(60)
	v_cvt_pk_bf16_f32 v15, v25, v26
	s_waitcnt vmcnt(58)
	v_cvt_pk_bf16_f32 v16, v27, v28
	s_waitcnt vmcnt(56)
	v_cvt_pk_bf16_f32 v17, v29, v40
	ds_write_b128 v45, v[14:17]
	s_waitcnt vmcnt(54)
	v_cvt_pk_bf16_f32 v14, v41, v42
	s_waitcnt vmcnt(52)
	v_cvt_pk_bf16_f32 v15, v43, v49
	s_waitcnt vmcnt(50)
	v_cvt_pk_bf16_f32 v16, v50, v51
	s_waitcnt vmcnt(48)
	v_cvt_pk_bf16_f32 v17, v52, v53
	ds_write_b128 v45, v[14:17] offset:16
	s_waitcnt vmcnt(46)
	v_cvt_pk_bf16_f32 v14, v54, v55
	s_waitcnt vmcnt(44)
	v_cvt_pk_bf16_f32 v15, v56, v57
	v_ashrrev_i32_e32 v21, 31, v20
	v_lshlrev_b64 v[36:37], 19, v[20:21]
	s_waitcnt vmcnt(42)
	v_cvt_pk_bf16_f32 v16, v58, v59
	v_lshl_add_u64 v[30:31], v[30:31], 0, v[36:37]
	s_waitcnt vmcnt(40)
	v_cvt_pk_bf16_f32 v17, v60, v61
	ds_write_b128 v46, v[14:17]
	s_waitcnt vmcnt(38)
	v_cvt_pk_bf16_f32 v14, v62, v63
	s_waitcnt vmcnt(36)
	v_cvt_pk_bf16_f32 v15, v64, v65
	s_waitcnt vmcnt(34)
	v_cvt_pk_bf16_f32 v16, v66, v67
	s_waitcnt vmcnt(32)
	v_cvt_pk_bf16_f32 v17, v68, v69
	ds_write_b128 v46, v[14:17] offset:16
	ds_read_b128 v[14:17], v47
	ds_read_b128 v[18:21], v47 offset:1024
	ds_read_b128 v[22:25], v47 offset:2048
	ds_read_b128 v[26:29], v47 offset:3072
	s_waitcnt lgkmcnt(3)
	global_store_dwordx4 v[32:33], v[14:17], off
	s_waitcnt lgkmcnt(2)
	global_store_dwordx4 v[34:35], v[18:21], off
	s_waitcnt lgkmcnt(1)
	global_store_dwordx4 v[38:39], v[22:25], off
	s_waitcnt lgkmcnt(0)
	global_store_dwordx4 v[30:31], v[26:29], off
	s_waitcnt lgkmcnt(0)
	v_sub_u32_e32 v114, v122, v2
	v_ashrrev_i32_e32 v115, 4, v114
	v_add_u32_e32 v117, 32, v114
	v_and_b32_e32 v114, -2, v115
	v_ashrrev_i32_e32 v119, 4, v117
	v_or_b32_e32 v116, 1, v115
	v_ashrrev_i32_e32 v115, 31, v114
	v_and_b32_e32 v118, -2, v119
	v_ashrrev_i32_e32 v117, 31, v116
	v_or_b32_e32 v120, 1, v119
	v_lshlrev_b64 v[114:115], 19, v[114:115]
	v_ashrrev_i32_e32 v119, 31, v118
	v_lshlrev_b64 v[116:117], 19, v[116:117]
	v_lshl_add_u64 v[132:133], v[130:131], 0, v[114:115]
	v_lshlrev_b64 v[114:115], 19, v[118:119]
	v_lshl_add_u64 v[134:135], v[130:131], 0, v[116:117]
	v_lshl_add_u64 v[138:139], v[130:131], 0, v[114:115]
	s_waitcnt vmcnt(30)
	v_cvt_pk_bf16_f32 v114, v123, v124
	s_waitcnt vmcnt(28)
	v_cvt_pk_bf16_f32 v115, v125, v126
	s_waitcnt vmcnt(26)
	v_cvt_pk_bf16_f32 v116, v127, v128
	s_waitcnt vmcnt(24)
	v_cvt_pk_bf16_f32 v117, v129, v140
	ds_write_b128 v45, v[114:117]
	s_waitcnt vmcnt(22)
	v_cvt_pk_bf16_f32 v114, v141, v142
	s_waitcnt vmcnt(20)
	v_cvt_pk_bf16_f32 v115, v143, v149
	s_waitcnt vmcnt(18)
	v_cvt_pk_bf16_f32 v116, v150, v151
	s_waitcnt vmcnt(16)
	v_cvt_pk_bf16_f32 v117, v152, v153
	ds_write_b128 v45, v[114:117] offset:16
	s_waitcnt vmcnt(14)
	v_cvt_pk_bf16_f32 v114, v154, v155
	s_waitcnt vmcnt(12)
	v_cvt_pk_bf16_f32 v115, v156, v157
	v_ashrrev_i32_e32 v121, 31, v120
	v_lshlrev_b64 v[136:137], 19, v[120:121]
	s_waitcnt vmcnt(10)
	v_cvt_pk_bf16_f32 v116, v158, v159
	v_lshl_add_u64 v[130:131], v[130:131], 0, v[136:137]
	v_cmp_lt_u32_e32 vcc, s63, v113
	s_or_b64 s[46:47], vcc, s[46:47]
	s_waitcnt vmcnt(8)
	v_cvt_pk_bf16_f32 v117, v160, v161
	ds_write_b128 v46, v[114:117]
	s_waitcnt vmcnt(6)
	v_cvt_pk_bf16_f32 v114, v162, v163
	s_waitcnt vmcnt(4)
	v_cvt_pk_bf16_f32 v115, v164, v165
	s_waitcnt vmcnt(2)
	v_cvt_pk_bf16_f32 v116, v166, v167
	s_waitcnt vmcnt(0)
	v_cvt_pk_bf16_f32 v117, v168, v169
	ds_write_b128 v46, v[114:117] offset:16
	ds_read_b128 v[114:117], v47
	ds_read_b128 v[118:121], v47 offset:1024
	ds_read_b128 v[122:125], v47 offset:2048
	ds_read_b128 v[126:129], v47 offset:3072
	s_and_saveexec_b64 s[96:97], s[98:99]
	s_waitcnt lgkmcnt(3)
	global_store_dwordx4 v[132:133], v[114:117], off
	s_waitcnt lgkmcnt(2)
	global_store_dwordx4 v[134:135], v[118:121], off
	s_waitcnt lgkmcnt(1)
	global_store_dwordx4 v[138:139], v[122:125], off
	s_waitcnt lgkmcnt(0)
	global_store_dwordx4 v[130:131], v[126:129], off
	s_mov_b64 exec, s[96:97]
	s_waitcnt lgkmcnt(0)
	s_andn2_b64 exec, exec, s[46:47]
	s_cbranch_execnz .Lca_37

; template <int MODE, int K, int N>
; __device__ __forceinline__ void conv_blocked(const float* __restrict__ W, bf16* D, const float* __restrict__ gk, unsigned gtid, unsigned nthr, LAS unsigned char* scr  ) {
;     ...
;     for (unsigned it = gtid; it < items; it += nthr) {
;         const unsigned kb = it / (unsigned)N; const int n = (int)(it - kb * (unsigned)N), k0 = (int)kb * 32;
;         if (MODE == 1 && n >= C_U && n < C_GB) continue;
;         const float* src = W + (size_t)k0 * N + n;
;         float v[32];
; #pragma unroll
;         for (int i = 0; i < 32; ++i) v[i] = __builtin_nontemporal_load(src + (size_t)i * N);
.Lca_41:
	v_lshrrev_b32_e32 v51, 9, v49
	v_and_b32_e32 v52, 0xfe0, v51
	v_and_b32_e32 v50, 0x3fff, v49
	v_lshlrev_b32_e32 v6, 16, v52
	v_lshl_add_u64 v[12:13], s[44:45], 0, v[6:7]
	v_lshlrev_b32_e32 v6, 2, v50
	v_lshl_add_u64 v[36:37], v[12:13], 0, v[6:7]
	v_add_co_u32_e32 v14, vcc, 0x10000, v36
	s_nop 1
	v_addc_co_u32_e32 v15, vcc, 0, v37, vcc
	v_add_co_u32_e32 v16, vcc, 0x20000, v36
	s_nop 1
	v_addc_co_u32_e32 v17, vcc, 0, v37, vcc
	v_add_co_u32_e32 v18, vcc, 0x30000, v36
	s_nop 1
	v_addc_co_u32_e32 v19, vcc, 0, v37, vcc
	v_add_co_u32_e32 v20, vcc, 0x40000, v36
	s_nop 1
	v_addc_co_u32_e32 v21, vcc, 0, v37, vcc
	v_add_co_u32_e32 v22, vcc, 0x50000, v36
	s_nop 1
	v_addc_co_u32_e32 v23, vcc, 0, v37, vcc
	v_add_co_u32_e32 v24, vcc, 0x60000, v36
	s_nop 1
	v_addc_co_u32_e32 v25, vcc, 0, v37, vcc
	v_add_co_u32_e32 v26, vcc, 0x70000, v36
	s_nop 1
	v_addc_co_u32_e32 v27, vcc, 0, v37, vcc
	global_load_dword v12, v[36:37], off nt
	global_load_dword v13, v[14:15], off nt
	s_nop 0
	global_load_dword v14, v[16:17], off nt
	global_load_dword v15, v[18:19], off nt
	s_nop 0
	global_load_dword v16, v[20:21], off nt
	global_load_dword v17, v[22:23], off nt
	global_load_dword v18, v[24:25], off nt
	global_load_dword v19, v[26:27], off nt
	v_add_co_u32_e32 v20, vcc, s60, v36
	s_nop 1
	v_addc_co_u32_e32 v21, vcc, 0, v37, vcc
	v_add_co_u32_e32 v22, vcc, 0x90000, v36
	s_nop 1
	v_addc_co_u32_e32 v23, vcc, 0, v37, vcc
	v_add_co_u32_e32 v24, vcc, 0xa0000, v36
	s_nop 1
	v_addc_co_u32_e32 v25, vcc, 0, v37, vcc
	v_add_co_u32_e32 v26, vcc, 0xb0000, v36
	s_nop 1
	v_addc_co_u32_e32 v27, vcc, 0, v37, vcc
	v_add_co_u32_e32 v28, vcc, 0xc0000, v36
	s_nop 1
	v_addc_co_u32_e32 v29, vcc, 0, v37, vcc
	v_add_co_u32_e32 v30, vcc, 0xd0000, v36
	s_nop 1
	v_addc_co_u32_e32 v31, vcc, 0, v37, vcc
	v_add_co_u32_e32 v32, vcc, 0xe0000, v36
	s_nop 1
	v_addc_co_u32_e32 v33, vcc, 0, v37, vcc
	v_add_co_u32_e32 v34, vcc, 0xf0000, v36
	s_nop 1
	v_addc_co_u32_e32 v35, vcc, 0, v37, vcc
	global_load_dword v20, v[20:21], off nt
	s_nop 0
	global_load_dword v21, v[22:23], off nt
	s_nop 0
	global_load_dword v22, v[24:25], off nt
	global_load_dword v23, v[26:27], off nt
	s_nop 0
	global_load_dword v24, v[28:29], off nt
	global_load_dword v25, v[30:31], off nt
	global_load_dword v26, v[32:33], off nt
	global_load_dword v27, v[34:35], off nt
	v_add_co_u32_e32 v28, vcc, 0x100000, v36
	s_nop 1
	v_addc_co_u32_e32 v29, vcc, 0, v37, vcc
	v_add_co_u32_e32 v30, vcc, 0x110000, v36
	s_nop 1
	v_addc_co_u32_e32 v31, vcc, 0, v37, vcc
	v_add_co_u32_e32 v32, vcc, 0x120000, v36
	s_nop 1
	v_addc_co_u32_e32 v33, vcc, 0, v37, vcc
	v_add_co_u32_e32 v34, vcc, 0x130000, v36
	s_nop 1
	v_addc_co_u32_e32 v35, vcc, 0, v37, vcc
	v_add_co_u32_e32 v38, vcc, s61, v36
	s_nop 1
	v_addc_co_u32_e32 v39, vcc, 0, v37, vcc
	v_add_co_u32_e32 v40, vcc, 0x150000, v36
	s_nop 1
	v_addc_co_u32_e32 v41, vcc, 0, v37, vcc
	v_add_co_u32_e32 v42, vcc, 0x160000, v36
	s_nop 1
	v_addc_co_u32_e32 v43, vcc, 0, v37, vcc
	v_add_co_u32_e32 v54, vcc, 0x170000, v36
	s_nop 1
	v_addc_co_u32_e32 v55, vcc, 0, v37, vcc
	global_load_dword v28, v[28:29], off nt
	s_nop 0
	global_load_dword v29, v[30:31], off nt
	s_nop 0
	global_load_dword v30, v[32:33], off nt
	global_load_dword v31, v[34:35], off nt
	s_nop 0
	global_load_dword v32, v[38:39], off nt
	global_load_dword v33, v[40:41], off nt
	global_load_dword v34, v[42:43], off nt
	global_load_dword v35, v[54:55], off nt
	v_add_co_u32_e32 v38, vcc, 0x180000, v36
	s_nop 1
	v_addc_co_u32_e32 v39, vcc, 0, v37, vcc
	v_add_co_u32_e32 v40, vcc, 0x190000, v36
	s_nop 1
	v_addc_co_u32_e32 v41, vcc, 0, v37, vcc
	v_add_co_u32_e32 v42, vcc, 0x1a0000, v36
	s_nop 1
	v_addc_co_u32_e32 v43, vcc, 0, v37, vcc
	v_add_co_u32_e32 v54, vcc, 0x1b0000, v36
	s_nop 1
	v_addc_co_u32_e32 v55, vcc, 0, v37, vcc
	v_add_co_u32_e32 v56, vcc, 0x1c0000, v36
	s_nop 1
	v_addc_co_u32_e32 v57, vcc, 0, v37, vcc
	v_add_co_u32_e32 v58, vcc, 0x1d0000, v36
	s_nop 1
	v_addc_co_u32_e32 v59, vcc, 0, v37, vcc
	v_add_co_u32_e32 v60, vcc, 0x1e0000, v36
	s_nop 1
	v_addc_co_u32_e32 v61, vcc, 0, v37, vcc
	v_add_co_u32_e32 v62, vcc, 0x1f0000, v36
	s_nop 1
	v_addc_co_u32_e32 v63, vcc, 0, v37, vcc
	global_load_dword v36, v[38:39], off nt
	global_load_dword v37, v[40:41], off nt
	s_nop 0
	global_load_dword v38, v[42:43], off nt
	global_load_dword v39, v[54:55], off nt
	s_nop 0
	global_load_dword v42, v[56:57], off nt
	global_load_dword v43, v[58:59], off nt
	global_load_dword v40, v[60:61], off nt
	global_load_dword v41, v[62:63], off nt
	v_add_u32_e32 v149, s0, v49
	v_cmp_ge_u32_e32 vcc, s63, v149
	v_mov_b32_e32 v107, 0
	s_nop 0
	v_cndmask_b32_e32 v149, v49, v149, vcc
	s_mov_b64 s[98:99], vcc
	v_lshrrev_b32_e32 v151, 9, v149
	v_and_b32_e32 v152, 0xfe0, v151
	v_and_b32_e32 v150, 0x3fff, v149
	v_lshlrev_b32_e32 v106, 16, v152
	v_lshl_add_u64 v[112:113], s[44:45], 0, v[106:107]
	v_lshlrev_b32_e32 v106, 2, v150
	v_lshl_add_u64 v[136:137], v[112:113], 0, v[106:107]
	v_add_co_u32_e32 v114, vcc, 0x10000, v136
	s_nop 1
	v_addc_co_u32_e32 v115, vcc, 0, v137, vcc
	v_add_co_u32_e32 v116, vcc, 0x20000, v136
	s_nop 1
	v_addc_co_u32_e32 v117, vcc, 0, v137, vcc
	v_add_co_u32_e32 v118, vcc, 0x30000, v136
	s_nop 1
	v_addc_co_u32_e32 v119, vcc, 0, v137, vcc
	v_add_co_u32_e32 v120, vcc, 0x40000, v136
	s_nop 1
	v_addc_co_u32_e32 v121, vcc, 0, v137, vcc
	v_add_co_u32_e32 v122, vcc, 0x50000, v136
	s_nop 1
	v_addc_co_u32_e32 v123, vcc, 0, v137, vcc
	v_add_co_u32_e32 v124, vcc, 0x60000, v136
	s_nop 1
	v_addc_co_u32_e32 v125, vcc, 0, v137, vcc
	v_add_co_u32_e32 v126, vcc, 0x70000, v136
	s_nop 1
	v_addc_co_u32_e32 v127, vcc, 0, v137, vcc
	global_load_dword v112, v[136:137], off nt
; template <int MODE, int K, int N>
; __device__ __forceinline__ void conv_blocked(const float* __restrict__ W, bf16* D, const float* __restrict__ gk, unsigned gtid, unsigned nthr, LAS unsigned char* scr  ) {
;     ...
;         for (int i = 0; i < 32; ++i) v[i] = __builtin_nontemporal_load(src + (size_t)i * N);
;         if (gk) {
; #pragma unroll
;             for (int i = 0; i < 32; ++i) v[i] *= gk[k0 + i];
;         }
	global_load_dword v113, v[114:115], off nt
	s_nop 0
	global_load_dword v114, v[116:117], off nt
	global_load_dword v115, v[118:119], off nt
	s_nop 0
	global_load_dword v116, v[120:121], off nt
	global_load_dword v117, v[122:123], off nt
	global_load_dword v118, v[124:125], off nt
	global_load_dword v119, v[126:127], off nt
	v_add_co_u32_e32 v120, vcc, s60, v136
	s_nop 1
	v_addc_co_u32_e32 v121, vcc, 0, v137, vcc
	v_add_co_u32_e32 v122, vcc, 0x90000, v136
	s_nop 1
	v_addc_co_u32_e32 v123, vcc, 0, v137, vcc
	v_add_co_u32_e32 v124, vcc, 0xa0000, v136
	s_nop 1
	v_addc_co_u32_e32 v125, vcc, 0, v137, vcc
	v_add_co_u32_e32 v126, vcc, 0xb0000, v136
	s_nop 1
	v_addc_co_u32_e32 v127, vcc, 0, v137, vcc
	v_add_co_u32_e32 v128, vcc, 0xc0000, v136
	s_nop 1
	v_addc_co_u32_e32 v129, vcc, 0, v137, vcc
	v_add_co_u32_e32 v130, vcc, 0xd0000, v136
	s_nop 1
	v_addc_co_u32_e32 v131, vcc, 0, v137, vcc
	v_add_co_u32_e32 v132, vcc, 0xe0000, v136
	s_nop 1
	v_addc_co_u32_e32 v133, vcc, 0, v137, vcc
	v_add_co_u32_e32 v134, vcc, 0xf0000, v136
	s_nop 1
	v_addc_co_u32_e32 v135, vcc, 0, v137, vcc
	global_load_dword v120, v[120:121], off nt
	s_nop 0
	global_load_dword v121, v[122:123], off nt
	s_nop 0
	global_load_dword v122, v[124:125], off nt
	global_load_dword v123, v[126:127], off nt
	s_nop 0
	global_load_dword v124, v[128:129], off nt
	global_load_dword v125, v[130:131], off nt
	global_load_dword v126, v[132:133], off nt
	global_load_dword v127, v[134:135], off nt
	v_add_co_u32_e32 v128, vcc, 0x100000, v136
	s_nop 1
	v_addc_co_u32_e32 v129, vcc, 0, v137, vcc
	v_add_co_u32_e32 v130, vcc, 0x110000, v136
	s_nop 1
	v_addc_co_u32_e32 v131, vcc, 0, v137, vcc
	v_add_co_u32_e32 v132, vcc, 0x120000, v136
	s_nop 1
	v_addc_co_u32_e32 v133, vcc, 0, v137, vcc
	v_add_co_u32_e32 v134, vcc, 0x130000, v136
	s_nop 1
	v_addc_co_u32_e32 v135, vcc, 0, v137, vcc
	v_add_co_u32_e32 v138, vcc, s61, v136
	s_nop 1
	v_addc_co_u32_e32 v139, vcc, 0, v137, vcc
	v_add_co_u32_e32 v140, vcc, 0x150000, v136
	s_nop 1
	v_addc_co_u32_e32 v141, vcc, 0, v137, vcc
	v_add_co_u32_e32 v142, vcc, 0x160000, v136
	s_nop 1
	v_addc_co_u32_e32 v143, vcc, 0, v137, vcc
	v_add_co_u32_e32 v154, vcc, 0x170000, v136
	s_nop 1
	v_addc_co_u32_e32 v155, vcc, 0, v137, vcc
	global_load_dword v128, v[128:129], off nt
	s_nop 0
	global_load_dword v129, v[130:131], off nt
	s_nop 0
	global_load_dword v130, v[132:133], off nt
	global_load_dword v131, v[134:135], off nt
	s_nop 0
	global_load_dword v132, v[138:139], off nt
	global_load_dword v133, v[140:141], off nt
	global_load_dword v134, v[142:143], off nt
	global_load_dword v135, v[154:155], off nt
	v_add_co_u32_e32 v138, vcc, 0x180000, v136
	s_nop 1
	v_addc_co_u32_e32 v139, vcc, 0, v137, vcc
	v_add_co_u32_e32 v140, vcc, 0x190000, v136
	s_nop 1
	v_addc_co_u32_e32 v141, vcc, 0, v137, vcc
	v_add_co_u32_e32 v142, vcc, 0x1a0000, v136
	s_nop 1
	v_addc_co_u32_e32 v143, vcc, 0, v137, vcc
	v_add_co_u32_e32 v154, vcc, 0x1b0000, v136
	s_nop 1
	v_addc_co_u32_e32 v155, vcc, 0, v137, vcc
	v_add_co_u32_e32 v156, vcc, 0x1c0000, v136
	s_nop 1
	v_addc_co_u32_e32 v157, vcc, 0, v137, vcc
	v_add_co_u32_e32 v158, vcc, 0x1d0000, v136
	s_nop 1
	v_addc_co_u32_e32 v159, vcc, 0, v137, vcc
	v_add_co_u32_e32 v160, vcc, 0x1e0000, v136
	s_nop 1
	v_addc_co_u32_e32 v161, vcc, 0, v137, vcc
	v_add_co_u32_e32 v162, vcc, 0x1f0000, v136
	s_nop 1
	v_addc_co_u32_e32 v163, vcc, 0, v137, vcc
	global_load_dword v136, v[138:139], off nt
	global_load_dword v137, v[140:141], off nt
	s_nop 0
	global_load_dword v138, v[142:143], off nt
	global_load_dword v139, v[154:155], off nt
	s_nop 0
	s_waitcnt vmcnt(59)
	global_load_dword v142, v[156:157], off nt
	global_load_dword v143, v[158:159], off nt
	global_load_dword v140, v[160:161], off nt
	global_load_dword v141, v[162:163], off nt
	s_andn2_b64 vcc, exec, s[30:31]
	s_cbranch_vccnz .Lca_40
	s_waitcnt vmcnt(54)
	v_lshlrev_b32_e32 v6, 2, v52
	global_load_dwordx3 v[80:82], v6, s[46:47] offset:112
	global_load_dwordx4 v[52:55], v6, s[46:47]
	global_load_dwordx4 v[56:59], v6, s[46:47] offset:16
	global_load_dwordx4 v[60:63], v6, s[46:47] offset:32
	global_load_dwordx4 v[64:67], v6, s[46:47] offset:48
	global_load_dwordx4 v[68:71], v6, s[46:47] offset:64
	global_load_dwordx4 v[72:75], v6, s[46:47] offset:80
	global_load_dwordx4 v[76:79], v6, s[46:47] offset:96
	v_lshl_or_b32 v6, v51, 2, v48
	global_load_dword v83, v6, s[46:47]
	s_waitcnt vmcnt(8)
	v_pk_mul_f32 v[42:43], v[42:43], v[80:81]
	s_waitcnt vmcnt(7)
	v_pk_mul_f32 v[12:13], v[12:13], v[52:53]
	v_pk_mul_f32 v[14:15], v[14:15], v[54:55]
	s_waitcnt vmcnt(6)
	v_pk_mul_f32 v[16:17], v[16:17], v[56:57]
	v_pk_mul_f32 v[18:19], v[18:19], v[58:59]
	s_waitcnt vmcnt(5)
	v_pk_mul_f32 v[20:21], v[20:21], v[60:61]
	v_pk_mul_f32 v[22:23], v[22:23], v[62:63]
	s_waitcnt vmcnt(4)
	v_pk_mul_f32 v[24:25], v[24:25], v[64:65]
	v_pk_mul_f32 v[26:27], v[26:27], v[66:67]
	s_waitcnt vmcnt(3)
	v_pk_mul_f32 v[28:29], v[28:29], v[68:69]
	v_pk_mul_f32 v[30:31], v[30:31], v[70:71]
	s_waitcnt vmcnt(2)
	v_pk_mul_f32 v[32:33], v[32:33], v[72:73]
	v_pk_mul_f32 v[34:35], v[34:35], v[74:75]
	s_waitcnt vmcnt(1)
	v_pk_mul_f32 v[36:37], v[36:37], v[76:77]
	v_pk_mul_f32 v[38:39], v[38:39], v[78:79]
	s_waitcnt vmcnt(0)
	v_pk_mul_f32 v[40:41], v[40:41], v[82:83]
	v_lshlrev_b32_e32 v6, 2, v152
	global_load_dwordx3 v[80:82], v6, s[46:47] offset:112
	global_load_dwordx4 v[52:55], v6, s[46:47]
	global_load_dwordx4 v[56:59], v6, s[46:47] offset:16
	global_load_dwordx4 v[60:63], v6, s[46:47] offset:32
	global_load_dwordx4 v[64:67], v6, s[46:47] offset:48
	global_load_dwordx4 v[68:71], v6, s[46:47] offset:64
	global_load_dwordx4 v[72:75], v6, s[46:47] offset:80
	global_load_dwordx4 v[76:79], v6, s[46:47] offset:96
	v_lshl_or_b32 v6, v151, 2, v48
	global_load_dword v83, v6, s[46:47]
	s_waitcnt vmcnt(8)
	v_pk_mul_f32 v[142:143], v[142:143], v[80:81]
	s_waitcnt vmcnt(7)
	v_pk_mul_f32 v[112:113], v[112:113], v[52:53]
	v_pk_mul_f32 v[114:115], v[114:115], v[54:55]
	s_waitcnt vmcnt(6)
	v_pk_mul_f32 v[116:117], v[116:117], v[56:57]
	v_pk_mul_f32 v[118:119], v[118:119], v[58:59]
	s_waitcnt vmcnt(5)
	v_pk_mul_f32 v[120:121], v[120:121], v[60:61]
	v_pk_mul_f32 v[122:123], v[122:123], v[62:63]
	s_waitcnt vmcnt(4)
	v_pk_mul_f32 v[124:125], v[124:125], v[64:65]
	v_pk_mul_f32 v[126:127], v[126:127], v[66:67]
	s_waitcnt vmcnt(3)
	v_pk_mul_f32 v[128:129], v[128:129], v[68:69]
	v_pk_mul_f32 v[130:131], v[130:131], v[70:71]
	s_waitcnt vmcnt(2)
	v_pk_mul_f32 v[132:133], v[132:133], v[72:73]
	v_pk_mul_f32 v[134:135], v[134:135], v[74:75]
	s_waitcnt vmcnt(1)
	v_pk_mul_f32 v[136:137], v[136:137], v[76:77]
	v_pk_mul_f32 v[138:139], v[138:139], v[78:79]
	s_waitcnt vmcnt(0)
	v_pk_mul_f32 v[140:141], v[140:141], v[82:83]
; __device__ __forceinline__ unsigned cvt_pk_bf16(float lo, float hi) { f32x2 v = {lo, hi}; bf16x2_t b = __builtin_convertvector(v, bf16x2_t); return __builtin_bit_cast(unsigned, b); }
; #define LAS __attribute__((address_space(3)))
; template <int MODE, int K, int N>
; __device__ __forceinline__ void conv_blocked(const float* __restrict__ W, bf16* D, const float* __restrict__ gk, unsigned gtid, unsigned nthr, LAS unsigned char* scr  ) {
;     ...
;         const int rho = pg8::p32inv(lane & 31), half = lane >> 5;
; #pragma unroll
;         for (int c = 0; c < 4; ++c) { v4u o; o.x = cvt_pk_bf16(v[8 * c], v[8 * c + 1]); o.y = cvt_pk_bf16(v[8 * c + 2], v[8 * c + 3]); o.z = cvt_pk_bf16(v[8 * c + 4], v[8 * c + 5]); o.w = cvt_pk_bf16(v[8 * c + 6], v[8 * c + 7]);
;             *(LAS v4u*)(scr + (half * 32 + rho) * 64 + ((c * 16) ^ ((rho & 8) << 2))) = o; }
;         const int nb = n - lane;
; #pragma unroll
;         for (int i = 0; i < 4; ++i) { const int h2 = i >> 1, b2 = i & 1; const int gp = ((MODE == 1) ? nperm(nb + 32 * h2) : nb + 32 * h2) & ~31;
;             const v4u o = *(const LAS v4u*)(scr + (h2 * 32 + b2 * 16) * 64 + lane * 16);
;             *(v4u*)((unsigned char*)D + ((size_t)((gp >> 4) + b2) * (K >> 5) + (size_t)(k0 >> 5)) * 1024 + lane * 16) = o; }
;         asm volatile("s_waitcnt lgkmcnt(0)" ::: "memory");
.Lca_40:
	s_waitcnt vmcnt(62)
	v_cvt_pk_bf16_f32 v12, v12, v13
	s_waitcnt vmcnt(60)
	v_cvt_pk_bf16_f32 v13, v14, v15
	s_waitcnt vmcnt(58)
	v_cvt_pk_bf16_f32 v14, v16, v17
	s_waitcnt vmcnt(56)
	v_cvt_pk_bf16_f32 v15, v18, v19
	ds_write_b128 v45, v[12:15]
	s_waitcnt vmcnt(54)
	v_cvt_pk_bf16_f32 v12, v20, v21
	s_waitcnt vmcnt(52)
	v_cvt_pk_bf16_f32 v13, v22, v23
	s_waitcnt vmcnt(50)
	v_cvt_pk_bf16_f32 v14, v24, v25
	s_waitcnt vmcnt(48)
	v_cvt_pk_bf16_f32 v15, v26, v27
	ds_write_b128 v45, v[12:15] offset:16
	s_waitcnt vmcnt(46)
	v_cvt_pk_bf16_f32 v12, v28, v29
	s_waitcnt vmcnt(44)
	v_cvt_pk_bf16_f32 v13, v30, v31
	s_waitcnt vmcnt(42)
	v_cvt_pk_bf16_f32 v14, v32, v33
	s_waitcnt vmcnt(40)
	v_cvt_pk_bf16_f32 v15, v34, v35
	ds_write_b128 v46, v[12:15]
	s_waitcnt vmcnt(38)
	v_cvt_pk_bf16_f32 v12, v36, v37
	s_waitcnt vmcnt(36)
	v_cvt_pk_bf16_f32 v13, v38, v39
	s_waitcnt vmcnt(34)
	v_cvt_pk_bf16_f32 v14, v42, v43
	s_waitcnt vmcnt(32)
	v_cvt_pk_bf16_f32 v15, v40, v41
	v_lshrrev_b32_e32 v6, 4, v49
	ds_write_b128 v46, v[12:15] offset:16
	v_sub_u32_e32 v24, v50, v2
	v_and_b32_e32 v6, 0x1fc00, v6
	v_lshl_add_u64 v[20:21], v[10:11], 0, v[6:7]
	ds_read_b128 v[12:15], v47
	v_ashrrev_i32_e32 v6, 4, v24
	v_and_b32_e32 v16, -2, v6
	v_ashrrev_i32_e32 v17, 31, v16
	v_lshlrev_b64 v[16:17], 17, v[16:17]
	v_lshl_add_u64 v[22:23], v[20:21], 0, v[16:17]
	ds_read_b128 v[16:19], v47 offset:1024
	s_waitcnt lgkmcnt(1)
	global_store_dwordx4 v[22:23], v[12:15], off
	s_nop 1
	v_or_b32_e32 v12, 1, v6
	v_ashrrev_i32_e32 v13, 31, v12
	v_lshlrev_b64 v[12:13], 17, v[12:13]
	v_lshl_add_u64 v[12:13], v[20:21], 0, v[12:13]
	v_add_u32_e32 v6, 32, v24
	s_waitcnt lgkmcnt(0)
	global_store_dwordx4 v[12:13], v[16:19], off
	ds_read_b128 v[12:15], v47 offset:2048
	v_ashrrev_i32_e32 v6, 4, v6
	v_and_b32_e32 v16, -2, v6
	v_ashrrev_i32_e32 v17, 31, v16
	v_lshlrev_b64 v[16:17], 17, v[16:17]
	v_lshl_add_u64 v[22:23], v[20:21], 0, v[16:17]
	ds_read_b128 v[16:19], v47 offset:3072
	s_waitcnt lgkmcnt(1)
	global_store_dwordx4 v[22:23], v[12:15], off
	s_nop 0
	s_nop 0
	v_or_b32_e32 v12, 1, v6
	v_ashrrev_i32_e32 v13, 31, v12
	v_lshlrev_b64 v[12:13], 17, v[12:13]
	v_lshl_add_u64 v[12:13], v[20:21], 0, v[12:13]
	s_waitcnt lgkmcnt(0)
	global_store_dwordx4 v[12:13], v[16:19], off
	s_waitcnt lgkmcnt(0)
	s_waitcnt vmcnt(30)
	v_cvt_pk_bf16_f32 v112, v112, v113
	s_waitcnt vmcnt(28)
	v_cvt_pk_bf16_f32 v113, v114, v115
	s_waitcnt vmcnt(26)
	v_cvt_pk_bf16_f32 v114, v116, v117
	s_waitcnt vmcnt(24)
	v_cvt_pk_bf16_f32 v115, v118, v119
	ds_write_b128 v45, v[112:115]
	s_waitcnt vmcnt(22)
	v_cvt_pk_bf16_f32 v112, v120, v121
	s_waitcnt vmcnt(20)
	v_cvt_pk_bf16_f32 v113, v122, v123
	s_waitcnt vmcnt(18)
	v_cvt_pk_bf16_f32 v114, v124, v125
	s_waitcnt vmcnt(16)
	v_cvt_pk_bf16_f32 v115, v126, v127
	ds_write_b128 v45, v[112:115] offset:16
	s_waitcnt vmcnt(14)
	v_cvt_pk_bf16_f32 v112, v128, v129
	s_waitcnt vmcnt(12)
	v_cvt_pk_bf16_f32 v113, v130, v131
	s_waitcnt vmcnt(10)
	v_cvt_pk_bf16_f32 v114, v132, v133
	s_waitcnt vmcnt(8)
	v_cvt_pk_bf16_f32 v115, v134, v135
	ds_write_b128 v46, v[112:115]
	s_waitcnt vmcnt(6)
	v_cvt_pk_bf16_f32 v112, v136, v137
	s_waitcnt vmcnt(4)
	v_cvt_pk_bf16_f32 v113, v138, v139
	s_waitcnt vmcnt(2)
	v_cvt_pk_bf16_f32 v114, v142, v143
	s_waitcnt vmcnt(0)
	v_cvt_pk_bf16_f32 v115, v140, v141
	v_lshrrev_b32_e32 v106, 4, v149
	ds_write_b128 v46, v[112:115] offset:16
	v_sub_u32_e32 v124, v150, v2
	v_and_b32_e32 v106, 0x1fc00, v106
	v_lshl_add_u64 v[120:121], v[10:11], 0, v[106:107]
	ds_read_b128 v[112:115], v47
	v_ashrrev_i32_e32 v106, 4, v124
	v_and_b32_e32 v116, -2, v106
	v_ashrrev_i32_e32 v117, 31, v116
	v_lshlrev_b64 v[116:117], 17, v[116:117]
	v_lshl_add_u64 v[122:123], v[120:121], 0, v[116:117]
	ds_read_b128 v[116:119], v47 offset:1024
	s_waitcnt lgkmcnt(1)
	s_and_saveexec_b64 s[96:97], s[98:99]
	global_store_dwordx4 v[122:123], v[112:115], off
	s_mov_b64 exec, s[96:97]
	v_add_u32_e32 v149, s0, v149
	v_cmp_lt_u32_e32 vcc, s63, v149
	v_or_b32_e32 v112, 1, v106
	v_ashrrev_i32_e32 v113, 31, v112
	v_lshlrev_b64 v[112:113], 17, v[112:113]
	v_lshl_add_u64 v[112:113], v[120:121], 0, v[112:113]
	v_add_u32_e32 v106, 32, v124
	s_waitcnt lgkmcnt(0)
	s_and_saveexec_b64 s[96:97], s[98:99]
	global_store_dwordx4 v[112:113], v[116:119], off
	s_mov_b64 exec, s[96:97]
	ds_read_b128 v[112:115], v47 offset:2048
	v_ashrrev_i32_e32 v106, 4, v106
	v_and_b32_e32 v116, -2, v106
	v_ashrrev_i32_e32 v117, 31, v116
	v_lshlrev_b64 v[116:117], 17, v[116:117]
	v_lshl_add_u64 v[122:123], v[120:121], 0, v[116:117]
	ds_read_b128 v[116:119], v47 offset:3072
	s_waitcnt lgkmcnt(1)
	s_and_saveexec_b64 s[96:97], s[98:99]
	global_store_dwordx4 v[122:123], v[112:115], off
	s_mov_b64 exec, s[96:97]
	s_or_b64 s[48:49], vcc, s[48:49]
	s_nop 0
	v_or_b32_e32 v112, 1, v106
	v_ashrrev_i32_e32 v113, 31, v112
	v_lshlrev_b64 v[112:113], 17, v[112:113]
	v_lshl_add_u64 v[112:113], v[120:121], 0, v[112:113]
	s_waitcnt lgkmcnt(0)
	s_and_saveexec_b64 s[96:97], s[98:99]
	global_store_dwordx4 v[112:113], v[116:119], off
	s_mov_b64 exec, s[96:97]
	s_waitcnt lgkmcnt(0)
	v_mov_b32_e32 v49, v149
	s_andn2_b64 exec, exec, s[48:49]
	s_cbranch_execnz .Lca_41
.Lca_43:
	s_or_b64 exec, exec, s[2:3]
	s_and_saveexec_b64 s[2:3], s[6:7]
	s_cbranch_execz .Lca_46
	s_lshl_b64 s[44:45], s[28:29], 26
	s_add_u32 s44, s16, s44
	s_addc_u32 s45, s17, s45
	v_lshl_add_u64 v[10:11], v[8:9], 0, s[40:41]
	s_mov_b64 s[46:47], 0
	v_mov_b32_e32 v12, v3
	v_mov_b32_e32 v13, v1
	v_mov_b32_e32 v107, 0
; template <int MODE, int K, int N>
; __device__ __forceinline__ void conv_blocked(const float* __restrict__ W, bf16* D, const float* __restrict__ gk, unsigned gtid, unsigned nthr, LAS unsigned char* scr  ) {
;     ...
;     for (unsigned it = gtid; it < items; it += nthr) {
;         const unsigned kb = it / (unsigned)N; const int n = (int)(it - kb * (unsigned)N), k0 = (int)kb * 32;
;         if (MODE == 1 && n >= C_U && n < C_GB) continue;
;         const float* src = W + (size_t)k0 * N + n;
;         float v[32];
; #pragma unroll
;         for (int i = 0; i < 32; ++i) v[i] = __builtin_nontemporal_load(src + (size_t)i * N);
.Lca_45:
	v_and_b32_e32 v6, 0xfe0000, v12
	v_and_b32_e32 v22, 0xfff, v13
	v_lshlrev_b32_e32 v6, 2, v6
	v_lshl_add_u64 v[14:15], s[44:45], 0, v[6:7]
	v_lshlrev_b32_e32 v6, 2, v22
	v_lshl_add_u64 v[14:15], v[14:15], 0, v[6:7]
	v_add_co_u32_e32 v16, vcc, 0x4000, v14
	global_load_dword v23, v[14:15], off nt
	s_nop 0
	v_addc_co_u32_e32 v17, vcc, 0, v15, vcc
	v_add_co_u32_e32 v18, vcc, 0x8000, v14
	global_load_dword v24, v[16:17], off nt
	s_nop 0
	v_addc_co_u32_e32 v19, vcc, 0, v15, vcc
	v_add_co_u32_e32 v16, vcc, 0xc000, v14
	v_lshrrev_b32_e32 v6, 2, v13
	s_nop 0
	v_addc_co_u32_e32 v17, vcc, 0, v15, vcc
	v_add_co_u32_e32 v20, vcc, 0x10000, v14
	global_load_dword v25, v[18:19], off nt
	global_load_dword v26, v[16:17], off nt
	v_addc_co_u32_e32 v21, vcc, 0, v15, vcc
	v_add_co_u32_e32 v16, vcc, 0x14000, v14
	v_and_b32_e32 v6, 0x1fc00, v6
	s_nop 0
	v_addc_co_u32_e32 v17, vcc, 0, v15, vcc
	v_add_co_u32_e32 v18, vcc, 0x18000, v14
	global_load_dword v27, v[20:21], off nt
	global_load_dword v28, v[16:17], off nt
	v_addc_co_u32_e32 v19, vcc, 0, v15, vcc
	v_add_co_u32_e32 v16, vcc, 0x1c000, v14
	v_lshl_add_u64 v[30:31], v[10:11], 0, v[6:7]
	s_nop 0
	v_addc_co_u32_e32 v17, vcc, 0, v15, vcc
	v_add_co_u32_e32 v20, vcc, 0x20000, v14
	global_load_dword v29, v[18:19], off nt
	global_load_dword v40, v[16:17], off nt
	v_addc_co_u32_e32 v21, vcc, 0, v15, vcc
	v_add_co_u32_e32 v16, vcc, 0x24000, v14
	v_add_u32_e32 v13, s0, v13
	s_nop 0
	v_addc_co_u32_e32 v17, vcc, 0, v15, vcc
	v_add_co_u32_e32 v18, vcc, 0x28000, v14
	global_load_dword v41, v[20:21], off nt
	global_load_dword v42, v[16:17], off nt
	v_addc_co_u32_e32 v19, vcc, 0, v15, vcc
	v_add_co_u32_e32 v16, vcc, 0x2c000, v14
	v_add_u32_e32 v12, s62, v12
	s_nop 0
	v_addc_co_u32_e32 v17, vcc, 0, v15, vcc
	v_add_co_u32_e32 v20, vcc, 0x30000, v14
	global_load_dword v43, v[18:19], off nt
	global_load_dword v49, v[16:17], off nt
	v_addc_co_u32_e32 v21, vcc, 0, v15, vcc
	v_add_co_u32_e32 v16, vcc, 0x34000, v14
	s_nop 1
	v_addc_co_u32_e32 v17, vcc, 0, v15, vcc
	v_add_co_u32_e32 v18, vcc, 0x38000, v14
	global_load_dword v50, v[20:21], off nt
	global_load_dword v51, v[16:17], off nt
	v_addc_co_u32_e32 v19, vcc, 0, v15, vcc
	v_add_co_u32_e32 v16, vcc, 0x3c000, v14
	s_nop 1
	v_addc_co_u32_e32 v17, vcc, 0, v15, vcc
	v_add_co_u32_e32 v20, vcc, 0x40000, v14
	global_load_dword v52, v[18:19], off nt
	global_load_dword v53, v[16:17], off nt
	v_addc_co_u32_e32 v21, vcc, 0, v15, vcc
	v_add_co_u32_e32 v16, vcc, 0x44000, v14
	s_nop 1
	v_addc_co_u32_e32 v17, vcc, 0, v15, vcc
	v_add_co_u32_e32 v18, vcc, 0x48000, v14
	global_load_dword v54, v[20:21], off nt
	global_load_dword v55, v[16:17], off nt
	v_addc_co_u32_e32 v19, vcc, 0, v15, vcc
	v_add_co_u32_e32 v16, vcc, 0x4c000, v14
	s_nop 1
	v_addc_co_u32_e32 v17, vcc, 0, v15, vcc
	v_add_co_u32_e32 v20, vcc, 0x50000, v14
	global_load_dword v56, v[18:19], off nt
	global_load_dword v57, v[16:17], off nt
	v_addc_co_u32_e32 v21, vcc, 0, v15, vcc
	v_add_co_u32_e32 v16, vcc, 0x54000, v14
	s_nop 1
	v_addc_co_u32_e32 v17, vcc, 0, v15, vcc
	v_add_co_u32_e32 v18, vcc, 0x58000, v14
	global_load_dword v58, v[20:21], off nt
	global_load_dword v59, v[16:17], off nt
	v_addc_co_u32_e32 v19, vcc, 0, v15, vcc
	v_add_co_u32_e32 v16, vcc, 0x5c000, v14
	s_nop 1
	v_addc_co_u32_e32 v17, vcc, 0, v15, vcc
	v_add_co_u32_e32 v20, vcc, 0x60000, v14
	global_load_dword v60, v[18:19], off nt
	global_load_dword v61, v[16:17], off nt
	v_addc_co_u32_e32 v21, vcc, 0, v15, vcc
	v_add_co_u32_e32 v16, vcc, 0x64000, v14
	s_nop 1
	v_addc_co_u32_e32 v17, vcc, 0, v15, vcc
	v_add_co_u32_e32 v18, vcc, 0x68000, v14
	global_load_dword v62, v[20:21], off nt
	global_load_dword v63, v[16:17], off nt
	v_addc_co_u32_e32 v19, vcc, 0, v15, vcc
	v_add_co_u32_e32 v16, vcc, 0x6c000, v14
	s_nop 1
	v_addc_co_u32_e32 v17, vcc, 0, v15, vcc
	v_add_co_u32_e32 v20, vcc, 0x70000, v14
	global_load_dword v64, v[18:19], off nt
	global_load_dword v65, v[16:17], off nt
	v_addc_co_u32_e32 v21, vcc, 0, v15, vcc
	v_add_co_u32_e32 v16, vcc, 0x74000, v14
	s_nop 1
	v_addc_co_u32_e32 v17, vcc, 0, v15, vcc
	v_add_co_u32_e32 v18, vcc, 0x78000, v14
	global_load_dword v66, v[20:21], off nt
	global_load_dword v67, v[16:17], off nt
	v_addc_co_u32_e32 v19, vcc, 0, v15, vcc
	v_add_co_u32_e32 v14, vcc, 0x7c000, v14
	s_nop 1
	v_addc_co_u32_e32 v15, vcc, 0, v15, vcc
	global_load_dword v68, v[18:19], off nt
	global_load_dword v69, v[14:15], off nt
	v_cmp_ge_u32_e32 vcc, s66, v13
	v_subrev_u32_e32 v112, s62, v12
	v_subrev_u32_e32 v113, s0, v13
	s_mov_b64 s[98:99], vcc
	v_cndmask_b32_e32 v112, v112, v12, vcc
	v_cndmask_b32_e32 v113, v113, v13, vcc
	v_add_u32_e32 v13, s0, v13
	v_add_u32_e32 v12, s62, v12
	v_and_b32_e32 v106, 0xfe0000, v112
	v_and_b32_e32 v122, 0xfff, v113
	v_lshlrev_b32_e32 v106, 2, v106
	v_lshl_add_u64 v[114:115], s[44:45], 0, v[106:107]
	v_lshlrev_b32_e32 v106, 2, v122
	v_lshl_add_u64 v[114:115], v[114:115], 0, v[106:107]
	v_add_co_u32_e32 v116, vcc, 0x4000, v114
	global_load_dword v123, v[114:115], off nt
	s_nop 0
	v_addc_co_u32_e32 v117, vcc, 0, v115, vcc
	v_add_co_u32_e32 v118, vcc, 0x8000, v114
	global_load_dword v124, v[116:117], off nt
	s_nop 0
	v_addc_co_u32_e32 v119, vcc, 0, v115, vcc
	v_add_co_u32_e32 v116, vcc, 0xc000, v114
	v_lshrrev_b32_e32 v106, 2, v113
	s_nop 0
	v_addc_co_u32_e32 v117, vcc, 0, v115, vcc
	v_add_co_u32_e32 v120, vcc, 0x10000, v114
	global_load_dword v125, v[118:119], off nt
	global_load_dword v126, v[116:117], off nt
	v_addc_co_u32_e32 v121, vcc, 0, v115, vcc
	v_add_co_u32_e32 v116, vcc, 0x14000, v114
	v_and_b32_e32 v106, 0x1fc00, v106
	s_nop 0
	v_addc_co_u32_e32 v117, vcc, 0, v115, vcc
	v_add_co_u32_e32 v118, vcc, 0x18000, v114
; __device__ __forceinline__ unsigned cvt_pk_bf16(float lo, float hi) { f32x2 v = {lo, hi}; bf16x2_t b = __builtin_convertvector(v, bf16x2_t); return __builtin_bit_cast(unsigned, b); }
; #define LAS __attribute__((address_space(3)))
; template <int MODE, int K, int N>
; __device__ __forceinline__ void conv_blocked(const float* __restrict__ W, bf16* D, const float* __restrict__ gk, unsigned gtid, unsigned nthr, LAS unsigned char* scr  ) {
;     ...
;     for (unsigned it = gtid; it < items; it += nthr) {
;         const unsigned kb = it / (unsigned)N; const int n = (int)(it - kb * (unsigned)N), k0 = (int)kb * 32;
;         if (MODE == 1 && n >= C_U && n < C_GB) continue;
;         const float* src = W + (size_t)k0 * N + n;
;         float v[32];
; #pragma unroll
;         for (int i = 0; i < 32; ++i) v[i] = __builtin_nontemporal_load(src + (size_t)i * N);
;         if (gk) {
; #pragma unroll
;             for (int i = 0; i < 32; ++i) v[i] *= gk[k0 + i];
;         }
;         const int rho = pg8::p32inv(lane & 31), half = lane >> 5;
; #pragma unroll
;         for (int c = 0; c < 4; ++c) { v4u o; o.x = cvt_pk_bf16(v[8 * c], v[8 * c + 1]); o.y = cvt_pk_bf16(v[8 * c + 2], v[8 * c + 3]); o.z = cvt_pk_bf16(v[8 * c + 4], v[8 * c + 5]); o.w = cvt_pk_bf16(v[8 * c + 6], v[8 * c + 7]);
;             *(LAS v4u*)(scr + (half * 32 + rho) * 64 + ((c * 16) ^ ((rho & 8) << 2))) = o; }
;         const int nb = n - lane;
; #pragma unroll
;         for (int i = 0; i < 4; ++i) { const int h2 = i >> 1, b2 = i & 1; const int gp = ((MODE == 1) ? nperm(nb + 32 * h2) : nb + 32 * h2) & ~31;
;             const v4u o = *(const LAS v4u*)(scr + (h2 * 32 + b2 * 16) * 64 + lane * 16);
;             *(v4u*)((unsigned char*)D + ((size_t)((gp >> 4) + b2) * (K >> 5) + (size_t)(k0 >> 5)) * 1024 + lane * 16) = o; }
	global_load_dword v127, v[120:121], off nt
	global_load_dword v128, v[116:117], off nt
	v_addc_co_u32_e32 v119, vcc, 0, v115, vcc
	v_add_co_u32_e32 v116, vcc, 0x1c000, v114
	v_lshl_add_u64 v[130:131], v[10:11], 0, v[106:107]
	s_nop 0
	v_addc_co_u32_e32 v117, vcc, 0, v115, vcc
	v_add_co_u32_e32 v120, vcc, 0x20000, v114
	global_load_dword v129, v[118:119], off nt
	global_load_dword v140, v[116:117], off nt
	v_addc_co_u32_e32 v121, vcc, 0, v115, vcc
	v_add_co_u32_e32 v116, vcc, 0x24000, v114
	v_add_u32_e32 v113, s0, v113
	s_nop 0
	v_addc_co_u32_e32 v117, vcc, 0, v115, vcc
	v_add_co_u32_e32 v118, vcc, 0x28000, v114
	global_load_dword v141, v[120:121], off nt
	global_load_dword v142, v[116:117], off nt
	v_addc_co_u32_e32 v119, vcc, 0, v115, vcc
	v_add_co_u32_e32 v116, vcc, 0x2c000, v114
	v_add_u32_e32 v112, s62, v112
	s_nop 0
	v_addc_co_u32_e32 v117, vcc, 0, v115, vcc
	v_add_co_u32_e32 v120, vcc, 0x30000, v114
	global_load_dword v143, v[118:119], off nt
	global_load_dword v149, v[116:117], off nt
	v_addc_co_u32_e32 v121, vcc, 0, v115, vcc
	v_add_co_u32_e32 v116, vcc, 0x34000, v114
	s_nop 1
	v_addc_co_u32_e32 v117, vcc, 0, v115, vcc
	v_add_co_u32_e32 v118, vcc, 0x38000, v114
	global_load_dword v150, v[120:121], off nt
	global_load_dword v151, v[116:117], off nt
	v_addc_co_u32_e32 v119, vcc, 0, v115, vcc
	v_add_co_u32_e32 v116, vcc, 0x3c000, v114
	s_nop 1
	v_addc_co_u32_e32 v117, vcc, 0, v115, vcc
	v_add_co_u32_e32 v120, vcc, 0x40000, v114
	global_load_dword v152, v[118:119], off nt
	global_load_dword v153, v[116:117], off nt
	v_addc_co_u32_e32 v121, vcc, 0, v115, vcc
	v_add_co_u32_e32 v116, vcc, 0x44000, v114
	s_nop 1
	v_addc_co_u32_e32 v117, vcc, 0, v115, vcc
	v_add_co_u32_e32 v118, vcc, 0x48000, v114
	global_load_dword v154, v[120:121], off nt
	global_load_dword v155, v[116:117], off nt
	v_addc_co_u32_e32 v119, vcc, 0, v115, vcc
	v_add_co_u32_e32 v116, vcc, 0x4c000, v114
	s_nop 1
	v_addc_co_u32_e32 v117, vcc, 0, v115, vcc
	v_add_co_u32_e32 v120, vcc, 0x50000, v114
	global_load_dword v156, v[118:119], off nt
	global_load_dword v157, v[116:117], off nt
	v_addc_co_u32_e32 v121, vcc, 0, v115, vcc
	v_add_co_u32_e32 v116, vcc, 0x54000, v114
	s_nop 1
	v_addc_co_u32_e32 v117, vcc, 0, v115, vcc
	v_add_co_u32_e32 v118, vcc, 0x58000, v114
	global_load_dword v158, v[120:121], off nt
	global_load_dword v159, v[116:117], off nt
	v_addc_co_u32_e32 v119, vcc, 0, v115, vcc
	v_add_co_u32_e32 v116, vcc, 0x5c000, v114
	s_nop 1
	v_addc_co_u32_e32 v117, vcc, 0, v115, vcc
	v_add_co_u32_e32 v120, vcc, 0x60000, v114
	global_load_dword v160, v[118:119], off nt
	global_load_dword v161, v[116:117], off nt
	v_addc_co_u32_e32 v121, vcc, 0, v115, vcc
	v_add_co_u32_e32 v116, vcc, 0x64000, v114
	s_nop 1
	v_addc_co_u32_e32 v117, vcc, 0, v115, vcc
	v_add_co_u32_e32 v118, vcc, 0x68000, v114
	global_load_dword v162, v[120:121], off nt
	global_load_dword v163, v[116:117], off nt
	v_addc_co_u32_e32 v119, vcc, 0, v115, vcc
	v_add_co_u32_e32 v116, vcc, 0x6c000, v114
	s_nop 1
	v_addc_co_u32_e32 v117, vcc, 0, v115, vcc
	v_add_co_u32_e32 v120, vcc, 0x70000, v114
	global_load_dword v164, v[118:119], off nt
	global_load_dword v165, v[116:117], off nt
	v_addc_co_u32_e32 v121, vcc, 0, v115, vcc
	v_add_co_u32_e32 v116, vcc, 0x74000, v114
	s_nop 1
	v_addc_co_u32_e32 v117, vcc, 0, v115, vcc
	v_add_co_u32_e32 v118, vcc, 0x78000, v114
	s_waitcnt vmcnt(59)
	global_load_dword v166, v[120:121], off nt
	global_load_dword v167, v[116:117], off nt
	v_addc_co_u32_e32 v119, vcc, 0, v115, vcc
	v_add_co_u32_e32 v114, vcc, 0x7c000, v114
	s_nop 1
	v_addc_co_u32_e32 v115, vcc, 0, v115, vcc
	global_load_dword v168, v[118:119], off nt
	global_load_dword v169, v[114:115], off nt
	v_sub_u32_e32 v14, v22, v2
	v_ashrrev_i32_e32 v15, 4, v14
	v_add_u32_e32 v17, 32, v14
	v_and_b32_e32 v14, -2, v15
	v_ashrrev_i32_e32 v19, 4, v17
	v_or_b32_e32 v16, 1, v15
	v_ashrrev_i32_e32 v15, 31, v14
	v_and_b32_e32 v18, -2, v19
	v_ashrrev_i32_e32 v17, 31, v16
	v_or_b32_e32 v20, 1, v19
	v_lshlrev_b64 v[14:15], 17, v[14:15]
	v_ashrrev_i32_e32 v19, 31, v18
	v_lshlrev_b64 v[16:17], 17, v[16:17]
	v_lshl_add_u64 v[32:33], v[30:31], 0, v[14:15]
	v_lshlrev_b64 v[14:15], 17, v[18:19]
	v_lshl_add_u64 v[34:35], v[30:31], 0, v[16:17]
	v_lshl_add_u64 v[38:39], v[30:31], 0, v[14:15]
	s_waitcnt vmcnt(62)
; __device__ __forceinline__ unsigned cvt_pk_bf16(float lo, float hi) { f32x2 v = {lo, hi}; bf16x2_t b = __builtin_convertvector(v, bf16x2_t); return __builtin_bit_cast(unsigned, b); }
; #define LAS __attribute__((address_space(3)))
; template <int MODE, int K, int N>
; __device__ __forceinline__ void conv_blocked(const float* __restrict__ W, bf16* D, const float* __restrict__ gk, unsigned gtid, unsigned nthr, LAS unsigned char* scr  ) {
;     ...
;         const int rho = pg8::p32inv(lane & 31), half = lane >> 5;
; #pragma unroll
;         for (int c = 0; c < 4; ++c) { v4u o; o.x = cvt_pk_bf16(v[8 * c], v[8 * c + 1]); o.y = cvt_pk_bf16(v[8 * c + 2], v[8 * c + 3]); o.z = cvt_pk_bf16(v[8 * c + 4], v[8 * c + 5]); o.w = cvt_pk_bf16(v[8 * c + 6], v[8 * c + 7]);
;             *(LAS v4u*)(scr + (half * 32 + rho) * 64 + ((c * 16) ^ ((rho & 8) << 2))) = o; }
;         const int nb = n - lane;
; #pragma unroll
;         for (int i = 0; i < 4; ++i) { const int h2 = i >> 1, b2 = i & 1; const int gp = ((MODE == 1) ? nperm(nb + 32 * h2) : nb + 32 * h2) & ~31;
;             const v4u o = *(const LAS v4u*)(scr + (h2 * 32 + b2 * 16) * 64 + lane * 16);
;             *(v4u*)((unsigned char*)D + ((size_t)((gp >> 4) + b2) * (K >> 5) + (size_t)(k0 >> 5)) * 1024 + lane * 16) = o; }
;         asm volatile("s_waitcnt lgkmcnt(0)" ::: "memory");
	v_cvt_pk_bf16_f32 v14, v23, v24
	s_waitcnt vmcnt(60)
	v_cvt_pk_bf16_f32 v15, v25, v26
	s_waitcnt vmcnt(58)
	v_cvt_pk_bf16_f32 v16, v27, v28
	s_waitcnt vmcnt(56)
	v_cvt_pk_bf16_f32 v17, v29, v40
	ds_write_b128 v45, v[14:17]
	s_waitcnt vmcnt(54)
	v_cvt_pk_bf16_f32 v14, v41, v42
	s_waitcnt vmcnt(52)
	v_cvt_pk_bf16_f32 v15, v43, v49
	s_waitcnt vmcnt(50)
	v_cvt_pk_bf16_f32 v16, v50, v51
	s_waitcnt vmcnt(48)
	v_cvt_pk_bf16_f32 v17, v52, v53
	ds_write_b128 v45, v[14:17] offset:16
	s_waitcnt vmcnt(46)
	v_cvt_pk_bf16_f32 v14, v54, v55
	s_waitcnt vmcnt(44)
	v_cvt_pk_bf16_f32 v15, v56, v57
	v_ashrrev_i32_e32 v21, 31, v20
	v_lshlrev_b64 v[36:37], 17, v[20:21]
	s_waitcnt vmcnt(42)
	v_cvt_pk_bf16_f32 v16, v58, v59
	v_lshl_add_u64 v[30:31], v[30:31], 0, v[36:37]
	s_waitcnt vmcnt(40)
	v_cvt_pk_bf16_f32 v17, v60, v61
	ds_write_b128 v46, v[14:17]
	s_waitcnt vmcnt(38)
	v_cvt_pk_bf16_f32 v14, v62, v63
	s_waitcnt vmcnt(36)
	v_cvt_pk_bf16_f32 v15, v64, v65
	s_waitcnt vmcnt(34)
	v_cvt_pk_bf16_f32 v16, v66, v67
	s_waitcnt vmcnt(32)
	v_cvt_pk_bf16_f32 v17, v68, v69
	ds_write_b128 v46, v[14:17] offset:16
	ds_read_b128 v[14:17], v47
	ds_read_b128 v[18:21], v47 offset:1024
	ds_read_b128 v[22:25], v47 offset:2048
	ds_read_b128 v[26:29], v47 offset:3072
	s_waitcnt lgkmcnt(3)
	global_store_dwordx4 v[32:33], v[14:17], off
	s_waitcnt lgkmcnt(2)
	global_store_dwordx4 v[34:35], v[18:21], off
	s_waitcnt lgkmcnt(1)
	global_store_dwordx4 v[38:39], v[22:25], off
	s_waitcnt lgkmcnt(0)
	global_store_dwordx4 v[30:31], v[26:29], off
	s_waitcnt lgkmcnt(0)
	v_sub_u32_e32 v114, v122, v2
	v_ashrrev_i32_e32 v115, 4, v114
	v_add_u32_e32 v117, 32, v114
	v_and_b32_e32 v114, -2, v115
	v_ashrrev_i32_e32 v119, 4, v117
	v_or_b32_e32 v116, 1, v115
	v_ashrrev_i32_e32 v115, 31, v114
	v_and_b32_e32 v118, -2, v119
	v_ashrrev_i32_e32 v117, 31, v116
	v_or_b32_e32 v120, 1, v119
	v_lshlrev_b64 v[114:115], 17, v[114:115]
	v_ashrrev_i32_e32 v119, 31, v118
	v_lshlrev_b64 v[116:117], 17, v[116:117]
	v_lshl_add_u64 v[132:133], v[130:131], 0, v[114:115]
	v_lshlrev_b64 v[114:115], 17, v[118:119]
	v_lshl_add_u64 v[134:135], v[130:131], 0, v[116:117]
	v_lshl_add_u64 v[138:139], v[130:131], 0, v[114:115]
	s_waitcnt vmcnt(30)
	v_cvt_pk_bf16_f32 v114, v123, v124
	s_waitcnt vmcnt(28)
	v_cvt_pk_bf16_f32 v115, v125, v126
	s_waitcnt vmcnt(26)
	v_cvt_pk_bf16_f32 v116, v127, v128
	s_waitcnt vmcnt(24)
	v_cvt_pk_bf16_f32 v117, v129, v140
	ds_write_b128 v45, v[114:117]
	s_waitcnt vmcnt(22)
	v_cvt_pk_bf16_f32 v114, v141, v142
	s_waitcnt vmcnt(20)
	v_cvt_pk_bf16_f32 v115, v143, v149
	s_waitcnt vmcnt(18)
	v_cvt_pk_bf16_f32 v116, v150, v151
	s_waitcnt vmcnt(16)
	v_cvt_pk_bf16_f32 v117, v152, v153
	ds_write_b128 v45, v[114:117] offset:16
	s_waitcnt vmcnt(14)
	v_cvt_pk_bf16_f32 v114, v154, v155
	s_waitcnt vmcnt(12)
	v_cvt_pk_bf16_f32 v115, v156, v157
	v_ashrrev_i32_e32 v121, 31, v120
	v_lshlrev_b64 v[136:137], 17, v[120:121]
	s_waitcnt vmcnt(10)
	v_cvt_pk_bf16_f32 v116, v158, v159
	v_lshl_add_u64 v[130:131], v[130:131], 0, v[136:137]
	v_cmp_lt_u32_e32 vcc, s66, v113
	s_or_b64 s[46:47], vcc, s[46:47]
	s_waitcnt vmcnt(8)
	v_cvt_pk_bf16_f32 v117, v160, v161
	ds_write_b128 v46, v[114:117]
	s_waitcnt vmcnt(6)
	v_cvt_pk_bf16_f32 v114, v162, v163
	s_waitcnt vmcnt(4)
	v_cvt_pk_bf16_f32 v115, v164, v165
	s_waitcnt vmcnt(2)
	v_cvt_pk_bf16_f32 v116, v166, v167
	s_waitcnt vmcnt(0)
	v_cvt_pk_bf16_f32 v117, v168, v169
	ds_write_b128 v46, v[114:117] offset:16
	ds_read_b128 v[114:117], v47
	ds_read_b128 v[118:121], v47 offset:1024
	ds_read_b128 v[122:125], v47 offset:2048
	ds_read_b128 v[126:129], v47 offset:3072
	s_and_saveexec_b64 s[96:97], s[98:99]
	s_waitcnt lgkmcnt(3)
	global_store_dwordx4 v[132:133], v[114:117], off
	s_waitcnt lgkmcnt(2)
	global_store_dwordx4 v[134:135], v[118:121], off
	s_waitcnt lgkmcnt(1)
	global_store_dwordx4 v[138:139], v[122:125], off
	s_waitcnt lgkmcnt(0)
	global_store_dwordx4 v[130:131], v[126:129], off
	s_mov_b64 exec, s[96:97]
	s_waitcnt lgkmcnt(0)
	s_andn2_b64 exec, exec, s[46:47]
	s_cbranch_execnz .Lca_45

; __device__ __forceinline__ unsigned xb_ld(unsigned* p)              { return __hip_atomic_load(p, __ATOMIC_RELAXED, __HIP_MEMORY_SCOPE_AGENT); }
; __device__ __forceinline__ unsigned xb_add(unsigned* p, unsigned v) { return __hip_atomic_fetch_add(p, v, __ATOMIC_RELAXED, __HIP_MEMORY_SCOPE_AGENT); }
; #define XB_SPIN(cond, bar) do { unsigned _sp = 0; while (cond) { __builtin_amdgcn_s_sleep(1); \
;     if ((++_sp & 255u) == 0u) { if (xb_ld(&(bar)[XB_TMO])) break; if (_sp > XB_SPIN_CAP) { atomicAdd(&(bar)[XB_TMO], 1u); break; } } } } while (0)
; __device__ __forceinline__ void xcd_barrier(const XcdBarrier& b) {
;     asm volatile("s_waitcnt vmcnt(0)" ::: "memory");
;     __syncthreads();
;     if (threadIdx.x == 0) {
;         unsigned* bar = b.bar;
;         __builtin_amdgcn_s_waitcnt(0);
;         unsigned nloc = b.st[0], nx = b.st[1];
;         if (nloc == 0u) { xcd_barrier_complete(bar, b.x, nloc, nx); b.st[0] = nloc; b.st[1] = nx; }
;         const unsigned old = xb_add(&bar[XB_XSUB(b.x)], 1u);
;         const unsigned gen = old / nloc;
;         if (old + 1u == (gen + 1u) * nloc) {
;             __builtin_amdgcn_fence(__ATOMIC_RELEASE, "agent");
;             asm volatile("s_waitcnt vmcnt(0)" ::: "memory");
;             const unsigned og = xb_add(&bar[XB_TOP], 1u);
;             const unsigned tg = og / nx;
;             if (og + 1u == (tg + 1u) * nx) xb_add(&bar[XB_TOPGEN], 1u);
;             else XB_SPIN(xb_ld(&bar[XB_TOPGEN]) == tg, bar);
;             __builtin_amdgcn_fence(__ATOMIC_ACQUIRE, "agent");
;             xb_add(&bar[XB_XGEN(b.x)], 1u);
;             asm volatile("s_waitcnt vmcnt(0)" ::: "memory");
;         } else {
;             XB_SPIN(xb_ld(&bar[XB_XGEN(b.x)]) == gen, bar);
;             __builtin_amdgcn_fence(__ATOMIC_ACQUIRE, "agent");
;             asm volatile("s_waitcnt vmcnt(0)" ::: "memory");
;         }
;     }
;     __syncthreads();
.LBB0_635:
	s_andn2_saveexec_b64 s[2:3], s[10:11]
	s_cbranch_execz .LBB0_655
	s_mov_b64 s[10:11], exec
	s_waitcnt lgkmcnt(0)
	s_mov_b64 s[6:7], exec
	v_mbcnt_lo_u32_b32 v2, s6, 0
	v_mbcnt_hi_u32_b32 v2, s7, v2
	v_cmp_eq_u32_e32 vcc, 0, v2
	s_waitcnt vmcnt(0)
	buffer_inv sc1
	s_and_saveexec_b64 s[10:11], vcc
	s_cbranch_execz .LBB0_654
	s_bcnt1_i32_b64 s0, s[6:7]
	v_mov_b32_e32 v2, s0
	v_mov_b32_e32 v3, 0x2000
	global_atomic_add v3, v2, s[8:9] offset:1024

; __device__ __forceinline__ unsigned xb_ld(unsigned* p)              { return __hip_atomic_load(p, __ATOMIC_RELAXED, __HIP_MEMORY_SCOPE_AGENT); }
; __device__ __forceinline__ unsigned xb_add(unsigned* p, unsigned v) { return __hip_atomic_fetch_add(p, v, __ATOMIC_RELAXED, __HIP_MEMORY_SCOPE_AGENT); }
; #define XB_SPIN(cond, bar) do { unsigned _sp = 0; while (cond) { __builtin_amdgcn_s_sleep(1); \
;     if ((++_sp & 255u) == 0u) { if (xb_ld(&(bar)[XB_TMO])) break; if (_sp > XB_SPIN_CAP) { atomicAdd(&(bar)[XB_TMO], 1u); break; } } } } while (0)
; __device__ __forceinline__ void xcd_barrier(const XcdBarrier& b) {
;     asm volatile("s_waitcnt vmcnt(0)" ::: "memory");
;     __syncthreads();
;     if (threadIdx.x == 0) {
;         unsigned* bar = b.bar;
;         __builtin_amdgcn_s_waitcnt(0);
;         unsigned nloc = b.st[0], nx = b.st[1];
;         if (nloc == 0u) { xcd_barrier_complete(bar, b.x, nloc, nx); b.st[0] = nloc; b.st[1] = nx; }
;         const unsigned old = xb_add(&bar[XB_XSUB(b.x)], 1u);
;         const unsigned gen = old / nloc;
;         if (old + 1u == (gen + 1u) * nloc) {
;             __builtin_amdgcn_fence(__ATOMIC_RELEASE, "agent");
;             asm volatile("s_waitcnt vmcnt(0)" ::: "memory");
;             const unsigned og = xb_add(&bar[XB_TOP], 1u);
;             const unsigned tg = og / nx;
;             if (og + 1u == (tg + 1u) * nx) xb_add(&bar[XB_TOPGEN], 1u);
;             else XB_SPIN(xb_ld(&bar[XB_TOPGEN]) == tg, bar);
;             __builtin_amdgcn_fence(__ATOMIC_ACQUIRE, "agent");
;             xb_add(&bar[XB_XGEN(b.x)], 1u);
;             asm volatile("s_waitcnt vmcnt(0)" ::: "memory");
;         } else {
;             XB_SPIN(xb_ld(&bar[XB_XGEN(b.x)]) == gen, bar);
;             __builtin_amdgcn_fence(__ATOMIC_ACQUIRE, "agent");
;             asm volatile("s_waitcnt vmcnt(0)" ::: "memory");
;         }
;     }
;     __syncthreads();
.LBB0_718:
	s_andn2_saveexec_b64 s[2:3], s[10:11]
	s_cbranch_execz .LBB0_738
	s_mov_b64 s[10:11], exec
	s_waitcnt lgkmcnt(0)
	s_mov_b64 s[6:7], exec
	v_mbcnt_lo_u32_b32 v2, s6, 0
	v_mbcnt_hi_u32_b32 v2, s7, v2
	v_cmp_eq_u32_e32 vcc, 0, v2
	s_waitcnt vmcnt(0)
	buffer_inv sc1
	s_and_saveexec_b64 s[10:11], vcc
	s_cbranch_execz .LBB0_737
	s_bcnt1_i32_b64 s1, s[6:7]
	v_mov_b32_e32 v2, s1
	v_mov_b32_e32 v3, 0x2000
	global_atomic_add v3, v2, s[8:9] offset:1024
